# convert_layer (in-loop): rotate per-job tile assignment so each converting workgroup gets 4 tiles (was up to 11)
# speedup vs baseline: 1.0561x; 1.0020x over previous
; __device__ __forceinline__ int ltid() { int t = threadIdx.x; asm volatile("" : "+v"(t)); return t; }
; __device__ __forceinline__ void convert_job(unsigned char* smem, const float* src, int ld, int col0, int mapkind, int N, int K, const float* scale, bf16_t* dst, int vb, int vG) {
;     const int tidx = ltid();
;     bf16_t* tile = (bf16_t*)smem;
;     const int w = tidx >> 6, lane = tidx & 63;
;     const int tn = N / 64, tk = K / 256, ntile = tn * tk;
;     for (int t = vb; t < ntile; t += vG) {
;         const int n0 = (t % tn) * 64, k0 = (t / tn) * 256;
;         const int np = n0 + lane; int sc;
;         if (mapkind == 0) sc = col0 + np;
; __device__ __forceinline__ void convert_layer(unsigned char* smem, const Params& P, int layer, int skip) {
;     ...
;     convert_job(smem, P.w_glu + (size_t)layer * 512 * 512, 512, 0, 0, 512, 512, nullptr, wb + W_GLU, vb, vG);
.LBB0_650:
	s_or_b64 exec, exec, s[24:25]
	v_readlane_b32 s4, v232, 43
	v_readlane_b32 s5, v232, 44
	s_mov_b32 s29, s75
	s_lshl_b64 s[40:41], s[28:29], 20
	v_readlane_b32 s100, v231, 40
	s_cmpk_eq_u32 s48, 0xf0
	s_cselect_b32 s101, 0x40, 0
	s_add_i32 s100, s100, s101
	s_sub_i32 s101, s100, s48
	s_cmp_ge_u32 s100, s48
	s_cselect_b32 s100, s101, s100
	s_cmpk_lt_u32 s100, 0x10
	s_cselect_b64 s[4:5], -1, 0
	v_cndmask_b32_e64 v0, 0, 1, s[4:5]
	v_mov_b32_e32 v16, v186
	v_cmp_ne_u32_e64 s[24:25], 1, v0
	s_andn2_b64 vcc, exec, s[4:5]
	s_cbranch_vccnz .LBB0_653
	v_ashrrev_i32_e32 v0, 1, v16
	v_and_b32_e32 v13, 0xffffffe0, v0
	v_lshlrev_b32_e32 v0, 4, v16
	v_and_b32_e32 v0, 0x1f0, v0
	v_and_b32_e32 v12, 63, v16
	v_and_b32_e32 v18, 0xffffffc0, v16
	v_add_u32_e32 v21, 0, v0
	v_lshl_add_u64 v[10:11], s[36:37], 0, v[0:1]
	v_ashrrev_i32_e32 v0, 5, v16
	v_add_u32_e32 v14, 0x200, v16
	v_add_u32_e32 v15, 0x400, v16
	v_add_u32_e32 v16, 0x600, v16
	s_movk_i32 s6, 0x204
	s_mov_b64 s[4:5], 0xb80000
	v_ashrrev_i32_e32 v14, 5, v14
	v_ashrrev_i32_e32 v15, 5, v15
	v_ashrrev_i32_e32 v16, 5, v16
	s_add_u32 s2, s2, s40
	v_mad_u32_u24 v17, v12, s6, 0
	v_lshl_add_u64 v[10:11], v[10:11], 0, s[4:5]
	v_mul_lo_u32 v19, v0, s6
	v_mul_lo_u32 v20, v14, s6
	v_mul_lo_u32 v22, v15, s6
	v_mul_lo_u32 v23, v16, s6
	s_mov_b32 s4, s100
	s_addc_u32 s3, s3, s41
	s_lshl_b32 s29, s4, 6
	s_lshl_b32 s33, s48, 6
	v_add_u32_e32 v17, v17, v18
	v_add_u32_e32 v18, v21, v19
	v_add_u32_e32 v19, v21, v20
	v_add_u32_e32 v20, v21, v22
	v_add_u32_e32 v21, v21, v23
	s_mov_b32 s42, s4
	v_readlane_b32 s5, v231, 41

; __device__ __forceinline__ int ltid() { int t = threadIdx.x; asm volatile("" : "+v"(t)); return t; }
; __device__ __forceinline__ void convert_job(unsigned char* smem, const float* src, int ld, int col0, int mapkind, int N, int K, const float* scale, bf16_t* dst, int vb, int vG) {
;     const int tidx = ltid();
;     bf16_t* tile = (bf16_t*)smem;
;     const int w = tidx >> 6, lane = tidx & 63;
;     const int tn = N / 64, tk = K / 256, ntile = tn * tk;
;     for (int t = vb; t < ntile; t += vG) {
;         const int n0 = (t % tn) * 64, k0 = (t / tn) * 256;
;         const int np = n0 + lane; int sc;
;         if (mapkind == 0) sc = col0 + np;
; __device__ __forceinline__ void convert_layer(unsigned char* smem, const Params& P, int layer, int skip) {
;     ...
;     for (int r = 0; r < 3; ++r) convert_job(smem, P.w_branch + ((size_t)layer * 3 + r) * 512 * 1024, 1024, 0, 0, 1024, 512, nullptr, wb + W_BR + (size_t)r * 1024 * 512, vb, vG);
.LBB0_653:
	s_mul_i32 s2, s28, 0x600000
	v_readlane_b32 s4, v232, 45
	s_mul_hi_u32 s3, s28, 0x600000
	s_add_u32 s2, s8, s2
	v_readlane_b32 s5, v232, 46
	s_addc_u32 s3, s9, s3
	v_mov_b32_e32 v16, v186
	v_readlane_b32 s100, v231, 40
	s_cmpk_eq_u32 s48, 0xf0
	s_cselect_b32 s101, 0x30, 0
	s_add_i32 s100, s100, s101
	s_sub_i32 s101, s100, s48
	s_cmp_ge_u32 s100, s48
	s_cselect_b32 s100, s101, s100
	s_cmpk_lt_u32 s100, 0x20
	s_cselect_b64 s[4:5], -1, 0
	s_and_b64 vcc, exec, s[4:5]
	s_cbranch_vccz .LBB0_656
	v_ashrrev_i32_e32 v0, 1, v16
	v_and_b32_e32 v13, 0xffffffe0, v0
	v_lshlrev_b32_e32 v0, 4, v16
	v_and_b32_e32 v0, 0x1f0, v0
	v_and_b32_e32 v12, 63, v16
	v_and_b32_e32 v18, 0xffffffc0, v16
	v_add_u32_e32 v21, 0, v0
	v_lshl_add_u64 v[10:11], s[36:37], 0, v[0:1]
	v_ashrrev_i32_e32 v0, 5, v16
	v_add_u32_e32 v14, 0x200, v16
	v_add_u32_e32 v15, 0x400, v16
	v_add_u32_e32 v16, 0x600, v16
	s_movk_i32 s6, 0x204
	s_mov_b64 s[4:5], 0xc00000
	v_ashrrev_i32_e32 v14, 5, v14
	v_ashrrev_i32_e32 v15, 5, v15
	v_ashrrev_i32_e32 v16, 5, v16
	v_mad_u32_u24 v17, v12, s6, 0
	v_lshl_add_u64 v[10:11], v[10:11], 0, s[4:5]
	v_mul_lo_u32 v19, v0, s6
	v_mul_lo_u32 v20, v14, s6
	v_mul_lo_u32 v22, v15, s6
	v_mul_lo_u32 v23, v16, s6
	s_mov_b32 s4, s100
	s_lshl_b32 s8, s4, 6
	s_lshl_b32 s9, s48, 6
	v_add_u32_e32 v17, v17, v18
	v_add_u32_e32 v18, v21, v19
	v_add_u32_e32 v19, v21, v20
	v_add_u32_e32 v20, v21, v22
	v_add_u32_e32 v21, v21, v23
	s_mov_b32 s29, s4
	v_readlane_b32 s5, v231, 41

; __device__ __forceinline__ int ltid() { int t = threadIdx.x; asm volatile("" : "+v"(t)); return t; }
; __device__ __forceinline__ void convert_job(unsigned char* smem, const float* src, int ld, int col0, int mapkind, int N, int K, const float* scale, bf16_t* dst, int vb, int vG) {
;     const int tidx = ltid();
;     bf16_t* tile = (bf16_t*)smem;
;     const int w = tidx >> 6, lane = tidx & 63;
;     const int tn = N / 64, tk = K / 256, ntile = tn * tk;
;     for (int t = vb; t < ntile; t += vG) {
;         const int n0 = (t % tn) * 64, k0 = (t / tn) * 256;
;         const int np = n0 + lane; int sc;
;         if (mapkind == 0) sc = col0 + np;
; __device__ __forceinline__ void convert_layer(unsigned char* smem, const Params& P, int layer, int skip) {
;     ...
;     for (int r = 0; r < 3; ++r) convert_job(smem, P.w_branch + ((size_t)layer * 3 + r) * 512 * 1024, 1024, 0, 0, 1024, 512, nullptr, wb + W_BR + (size_t)r * 1024 * 512, vb, vG);
.LBB0_656:
	v_readlane_b32 s4, v232, 45
	v_readlane_b32 s5, v232, 46
	v_mov_b32_e32 v16, v186
	v_readlane_b32 s100, v231, 40
	s_cmpk_eq_u32 s48, 0xf0
	s_cselect_b32 s101, 0x10, 0
	s_add_i32 s100, s100, s101
	s_sub_i32 s101, s100, s48
	s_cmp_ge_u32 s100, s48
	s_cselect_b32 s100, s101, s100
	s_cmpk_lt_u32 s100, 0x20
	s_cselect_b64 s[4:5], -1, 0
	s_andn2_b64 vcc, exec, s[4:5]
	v_cndmask_b32_e64 v0, 0, 1, s[4:5]
	v_cmp_ne_u32_e64 s[6:7], 1, v0
	s_cbranch_vccnz .LBB0_659
	v_ashrrev_i32_e32 v0, 1, v16
	v_and_b32_e32 v13, 0xffffffe0, v0
	v_lshlrev_b32_e32 v0, 4, v16
	v_and_b32_e32 v0, 0x1f0, v0
	v_and_b32_e32 v12, 63, v16
	v_and_b32_e32 v18, 0xffffffc0, v16
	v_add_u32_e32 v21, 0, v0
	v_lshl_add_u64 v[10:11], s[36:37], 0, v[0:1]
	v_ashrrev_i32_e32 v0, 5, v16
	v_add_u32_e32 v14, 0x200, v16
	v_add_u32_e32 v15, 0x400, v16
	v_add_u32_e32 v16, 0x600, v16
	s_movk_i32 s29, 0x204
	s_mov_b64 s[4:5], 0xd00000
	v_ashrrev_i32_e32 v14, 5, v14
	v_ashrrev_i32_e32 v15, 5, v15
	v_ashrrev_i32_e32 v16, 5, v16
	s_add_u32 s8, s2, 0x200000
	v_mad_u32_u24 v17, v12, s29, 0
	v_lshl_add_u64 v[10:11], v[10:11], 0, s[4:5]
	v_mul_lo_u32 v19, v0, s29
	v_mul_lo_u32 v20, v14, s29
	v_mul_lo_u32 v22, v15, s29
	v_mul_lo_u32 v23, v16, s29
	s_mov_b32 s4, s100
	s_addc_u32 s9, s3, 0
	s_lshl_b32 s29, s4, 6
	s_lshl_b32 s33, s48, 6
	v_add_u32_e32 v17, v17, v18
	v_add_u32_e32 v18, v21, v19
	v_add_u32_e32 v19, v21, v20
	v_add_u32_e32 v20, v21, v22
	v_add_u32_e32 v21, v21, v23
	s_mov_b32 s50, s4
	v_readlane_b32 s5, v231, 41

; __device__ __forceinline__ int ltid() { int t = threadIdx.x; asm volatile("" : "+v"(t)); return t; }
; __device__ __forceinline__ void convert_job(unsigned char* smem, const float* src, int ld, int col0, int mapkind, int N, int K, const float* scale, bf16_t* dst, int vb, int vG) {
;     const int tidx = ltid();
;     bf16_t* tile = (bf16_t*)smem;
;     const int w = tidx >> 6, lane = tidx & 63;
;     const int tn = N / 64, tk = K / 256, ntile = tn * tk;
;     for (int t = vb; t < ntile; t += vG) {
;         const int n0 = (t % tn) * 64, k0 = (t / tn) * 256;
;         const int np = n0 + lane; int sc;
;         if (mapkind == 0) sc = col0 + np;
; __device__ __forceinline__ void convert_layer(unsigned char* smem, const Params& P, int layer, int skip) {
;     ...
;     for (int r = 0; r < 3; ++r) convert_job(smem, P.w_branch + ((size_t)layer * 3 + r) * 512 * 1024, 1024, 0, 0, 1024, 512, nullptr, wb + W_BR + (size_t)r * 1024 * 512, vb, vG);
.LBB0_659:
	v_mov_b32_e32 v16, v186
	v_readlane_b32 s100, v231, 40
	s_cmpk_eq_u32 s48, 0xf0
	s_cselect_b32 s101, 0xe0, 0
	s_add_i32 s100, s100, s101
	s_sub_i32 s101, s100, s48
	s_cmp_ge_u32 s100, s48
	s_cselect_b32 s100, s101, s100
	s_cmpk_lt_u32 s100, 0x20
	s_cselect_b64 s[6:7], 0, -1
	s_and_b64 vcc, exec, s[6:7]
	s_cbranch_vccnz .LBB0_662
	v_ashrrev_i32_e32 v0, 1, v16
	v_and_b32_e32 v13, 0xffffffe0, v0
	v_lshlrev_b32_e32 v0, 4, v16
	v_and_b32_e32 v0, 0x1f0, v0
	v_and_b32_e32 v12, 63, v16
	v_and_b32_e32 v18, 0xffffffc0, v16
	v_add_u32_e32 v21, 0, v0
	v_lshl_add_u64 v[10:11], s[36:37], 0, v[0:1]
	v_ashrrev_i32_e32 v0, 5, v16
	v_add_u32_e32 v14, 0x200, v16
	v_add_u32_e32 v15, 0x400, v16
	v_add_u32_e32 v16, 0x600, v16
	s_movk_i32 s6, 0x204
	s_mov_b64 s[4:5], 0xe00000
	v_ashrrev_i32_e32 v14, 5, v14
	v_ashrrev_i32_e32 v15, 5, v15
	v_ashrrev_i32_e32 v16, 5, v16
	s_add_u32 s2, s2, 0x400000
	v_mad_u32_u24 v17, v12, s6, 0
	v_lshl_add_u64 v[10:11], v[10:11], 0, s[4:5]
	v_mul_lo_u32 v19, v0, s6
	v_mul_lo_u32 v20, v14, s6
	v_mul_lo_u32 v22, v15, s6
	v_mul_lo_u32 v23, v16, s6
	s_mov_b32 s4, s100
	s_addc_u32 s3, s3, 0
	s_lshl_b32 s8, s4, 6
	s_lshl_b32 s9, s48, 6
	v_add_u32_e32 v17, v17, v18
	v_add_u32_e32 v18, v21, v19
	v_add_u32_e32 v19, v21, v20
	v_add_u32_e32 v20, v21, v22
	v_add_u32_e32 v21, v21, v23
	s_mov_b32 s29, s4
	v_readlane_b32 s5, v231, 41

; __device__ __forceinline__ int ltid() { int t = threadIdx.x; asm volatile("" : "+v"(t)); return t; }
; __device__ __forceinline__ void convert_job(unsigned char* smem, const float* src, int ld, int col0, int mapkind, int N, int K, const float* scale, bf16_t* dst, int vb, int vG) {
;     const int tidx = ltid();
;     bf16_t* tile = (bf16_t*)smem;
;     const int w = tidx >> 6, lane = tidx & 63;
;     const int tn = N / 64, tk = K / 256, ntile = tn * tk;
;     for (int t = vb; t < ntile; t += vG) {
;         const int n0 = (t % tn) * 64, k0 = (t / tn) * 256;
;         const int np = n0 + lane; int sc;
;         if (mapkind == 0) sc = col0 + np;
; __device__ __forceinline__ void convert_layer(unsigned char* smem, const Params& P, int layer, int skip) {
;     ...
;     convert_job(smem, P.w_out + (size_t)layer * DM * DM, DM, 0, 0, DM, DM, nullptr, wb + W_OUT, vb, vG);
.LBB0_662:
	v_readlane_b32 s2, v232, 47
	v_readlane_b32 s3, v232, 48
	v_mov_b32_e32 v16, v186
	v_readlane_b32 s100, v231, 40
	s_cmpk_eq_u32 s48, 0xf0
	s_cselect_b32 s101, 0xc0, 0
	s_add_i32 s100, s100, s101
	s_sub_i32 s101, s100, s48
	s_cmp_ge_u32 s100, s48
	s_cselect_b32 s100, s101, s100
	s_cmpk_lt_u32 s100, 0x40
	s_cselect_b64 s[2:3], -1, 0
	s_and_b64 vcc, exec, s[2:3]
	s_cbranch_vccz .LBB0_665
	v_ashrrev_i32_e32 v0, 1, v16
	v_and_b32_e32 v13, 0xffffffe0, v0
	v_lshlrev_b32_e32 v0, 4, v16
	v_and_b32_e32 v0, 0x1f0, v0
	v_and_b32_e32 v12, 63, v16
	v_and_b32_e32 v18, 0xffffffc0, v16
	v_add_u32_e32 v21, 0, v0
	v_lshl_add_u64 v[10:11], s[36:37], 0, v[0:1]
	v_ashrrev_i32_e32 v0, 5, v16
	v_add_u32_e32 v14, 0x200, v16
	v_add_u32_e32 v15, 0x400, v16
	v_add_u32_e32 v16, 0x600, v16
	s_lshl_b64 s[2:3], s[40:41], 2
	s_movk_i32 s6, 0x204
	s_mov_b64 s[4:5], 0xf00000
	v_ashrrev_i32_e32 v14, 5, v14
	v_ashrrev_i32_e32 v15, 5, v15
	v_ashrrev_i32_e32 v16, 5, v16
	s_add_u32 s2, s10, s2
	v_mad_u32_u24 v17, v12, s6, 0
	v_lshl_add_u64 v[10:11], v[10:11], 0, s[4:5]
	v_mul_lo_u32 v19, v0, s6
	v_mul_lo_u32 v20, v14, s6
	v_mul_lo_u32 v22, v15, s6
	v_mul_lo_u32 v23, v16, s6
	s_mov_b32 s4, s100
	s_addc_u32 s3, s11, s3
	s_lshl_b32 s8, s4, 6
	s_lshl_b32 s9, s48, 6
	v_add_u32_e32 v17, v17, v18
	v_add_u32_e32 v18, v21, v19
	v_add_u32_e32 v19, v21, v20
	v_add_u32_e32 v20, v21, v22
	v_add_u32_e32 v21, v21, v23
	s_mov_b32 s10, s4
	v_readlane_b32 s5, v231, 41

; __device__ __forceinline__ int ltid() { int t = threadIdx.x; asm volatile("" : "+v"(t)); return t; }
; __device__ __forceinline__ void convert_job(unsigned char* smem, const float* src, int ld, int col0, int mapkind, int N, int K, const float* scale, bf16_t* dst, int vb, int vG) {
;     const int tidx = ltid();
;     bf16_t* tile = (bf16_t*)smem;
;     const int w = tidx >> 6, lane = tidx & 63;
;     const int tn = N / 64, tk = K / 256, ntile = tn * tk;
;     for (int t = vb; t < ntile; t += vG) {
;         const int n0 = (t % tn) * 64, k0 = (t / tn) * 256;
;         const int np = n0 + lane; int sc;
;         if (mapkind == 0) sc = col0 + np;
;         else if (mapkind == 2) { if (np >= 1024 && np < 2048) { const int pq = (np - 1024) >> 8, c = np & 255; sc = (c < 128) ? (1024 + pq * 128 + c) : (1536 + pq * 128 + (c - 128)); } else sc = np; }
;         else { const int pn = np >> 8, c = np & 255; sc = (c < 128) ? (pn * 128 + c) : (FFH + pn * 128 + (c - 128)); }
; __device__ __forceinline__ void convert_layer(unsigned char* smem, const Params& P, int layer, int skip) {
;     ...
;     convert_job(smem, P.w_ffn_in + (size_t)layer * DM * 2 * FFH, 2 * FFH, 0, 1, 2 * FFH, DM, P.norm_ffn + layer * DM, wb + W_FFI, vb, vG);
.LBB0_665:
	v_readlane_b32 s2, v232, 49
	v_readlane_b32 s3, v232, 50
	v_mov_b32_e32 v12, v186
	v_readlane_b32 s100, v231, 40
	s_cmpk_eq_u32 s48, 0xf0
	s_cselect_b32 s101, 0x80, 0
	s_add_i32 s100, s100, s101
	s_sub_i32 s101, s100, s48
	s_cmp_ge_u32 s100, s48
	s_cselect_b32 s100, s101, s100
	s_andn2_b64 vcc, exec, s[2:3]
	s_cbranch_vccnz .LBB0_670
	s_mul_i32 s2, s28, 0x1600000
	v_ashrrev_i32_e32 v0, 1, v12
	s_mul_hi_u32 s3, s28, 0x1600000
	s_add_u32 s2, s14, s2
	v_and_b32_e32 v47, 0xffffffe0, v0
	v_lshlrev_b32_e32 v0, 4, v12
	s_addc_u32 s3, s15, s3
	v_and_b32_e32 v0, 0x1f0, v0
	s_add_u32 s6, s12, s38
	v_and_b32_e32 v46, 63, v12
	v_and_b32_e32 v14, 0xffffffc0, v12
	v_add_u32_e32 v15, 0, v0
	v_lshl_add_u64 v[10:11], s[36:37], 0, v[0:1]
	v_ashrrev_i32_e32 v0, 5, v12
	v_add_u32_e32 v17, 0x200, v12
	v_add_u32_e32 v18, 0x400, v12
	v_add_u32_e32 v12, 0x600, v12
	s_addc_u32 s7, s13, s39
	s_movk_i32 s10, 0x204
	s_mov_b64 s[4:5], 0x1100000
	v_ashrrev_i32_e32 v48, 5, v17
	v_ashrrev_i32_e32 v49, 5, v18
	v_ashrrev_i32_e32 v50, 5, v12
	s_cmp_lg_u64 s[12:13], 0
	v_mad_u32_u24 v13, v46, s10, 0
	v_lshl_add_u64 v[10:11], v[10:11], 0, s[4:5]
	v_mul_lo_u32 v16, v0, s10
	v_mul_lo_u32 v17, v48, s10
	v_mul_lo_u32 v18, v49, s10
	v_mul_lo_u32 v12, v50, s10
	s_mov_b32 s4, s100
	s_cselect_b64 s[8:9], -1, 0
	s_lshl_b32 s12, s4, 6
	s_lshl_b32 s13, s48, 6
	s_lshl_b32 s14, s4, 5
	s_lshl_b32 s15, s48, 5
	v_add_u32_e32 v51, v13, v14
	v_add_u32_e32 v52, v15, v16
	v_add_u32_e32 v53, v15, v17
	v_add_u32_e32 v54, v15, v18
	v_add_u32_e32 v55, v15, v12
	s_mov_b32 s29, s4
	v_readlane_b32 s5, v231, 41
	s_branch .LBB0_668

; __device__ __forceinline__ int ltid() { int t = threadIdx.x; asm volatile("" : "+v"(t)); return t; }
; __device__ __forceinline__ void convert_job(unsigned char* smem, const float* src, int ld, int col0, int mapkind, int N, int K, const float* scale, bf16_t* dst, int vb, int vG) {
;     const int tidx = ltid();
;     bf16_t* tile = (bf16_t*)smem;
;     const int w = tidx >> 6, lane = tidx & 63;
;     const int tn = N / 64, tk = K / 256, ntile = tn * tk;
;     for (int t = vb; t < ntile; t += vG) {
;         const int n0 = (t % tn) * 64, k0 = (t / tn) * 256;
;         const int np = n0 + lane; int sc;
;         if (mapkind == 0) sc = col0 + np;
; __device__ __forceinline__ void convert_layer(unsigned char* smem, const Params& P, int layer, int skip) {
;     ...
;     convert_job(smem, P.w_ffn_out + (size_t)layer * FFH * DM, DM, 0, 0, DM, FFH, nullptr, wb + W_FFO, vb, vG);
.LBB0_670:
	v_mov_b32_e32 v16, v186
	v_readlane_b32 s100, v231, 40
	s_cmpk_eq_u32 s48, 0xf0
	s_cselect_b32 s101, 0x10, 0
	s_add_i32 s100, s100, s101
	s_sub_i32 s101, s100, s48
	s_cmp_ge_u32 s100, s48
	s_cselect_b32 s100, s101, s100
	s_cmpk_lt_u32 s100, 0xb0
	s_cselect_b64 s[26:27], 0, -1
	s_and_b64 vcc, exec, s[26:27]
	s_cbranch_vccnz .LBB0_673
	v_ashrrev_i32_e32 v0, 1, v16
	v_and_b32_e32 v13, 0xffffffe0, v0
	v_lshlrev_b32_e32 v0, 4, v16
	v_and_b32_e32 v0, 0x1f0, v0
	v_and_b32_e32 v12, 63, v16
	v_and_b32_e32 v18, 0xffffffc0, v16
	v_add_u32_e32 v21, 0, v0
	v_lshl_add_u64 v[10:11], s[36:37], 0, v[0:1]
	v_ashrrev_i32_e32 v0, 5, v16
	v_add_u32_e32 v14, 0x200, v16
	v_add_u32_e32 v15, 0x400, v16
	v_add_u32_e32 v16, 0x600, v16
	s_mul_i32 s2, s28, 0xb00000
	s_movk_i32 s6, 0x204
	s_mov_b64 s[4:5], 0x1c00000
	v_ashrrev_i32_e32 v14, 5, v14
	v_ashrrev_i32_e32 v15, 5, v15
	v_ashrrev_i32_e32 v16, 5, v16
	s_mul_hi_u32 s3, s28, 0xb00000
	s_add_u32 s2, s16, s2
	v_mad_u32_u24 v17, v12, s6, 0
	v_lshl_add_u64 v[10:11], v[10:11], 0, s[4:5]
	v_mul_lo_u32 v19, v0, s6
	v_mul_lo_u32 v20, v14, s6
	v_mul_lo_u32 v22, v15, s6
	v_mul_lo_u32 v23, v16, s6
	s_mov_b32 s4, s100
	s_addc_u32 s3, s17, s3
	s_lshl_b32 s8, s4, 6
	s_lshl_b32 s9, s48, 6
	v_add_u32_e32 v17, v17, v18
	v_add_u32_e32 v18, v21, v19
	v_add_u32_e32 v19, v21, v20
	v_add_u32_e32 v20, v21, v22
	v_add_u32_e32 v21, v21, v23
	s_mov_b32 s10, s4
	v_readlane_b32 s5, v231, 41

; __device__ __forceinline__ int ltid() { int t = threadIdx.x; asm volatile("" : "+v"(t)); return t; }
; __device__ __forceinline__ void convert_job(unsigned char* smem, const float* src, int ld, int col0, int mapkind, int N, int K, const float* scale, bf16_t* dst, int vb, int vG) {
;     const int tidx = ltid();
;     bf16_t* tile = (bf16_t*)smem;
;     const int w = tidx >> 6, lane = tidx & 63;
;     const int tn = N / 64, tk = K / 256, ntile = tn * tk;
;     for (int t = vb; t < ntile; t += vG) {
;         const int n0 = (t % tn) * 64, k0 = (t / tn) * 256;
;         const int np = n0 + lane; int sc;
;         if (mapkind == 0) sc = col0 + np;
; __device__ __forceinline__ void convert_layer(unsigned char* smem, const Params& P, int layer, int skip) {
;     ...
;     convert_job(smem, P.w_ple_gate + (size_t)layer * DM * DM, DM, 0, 0, DM, DM, P.norm_ple + layer * DM, wb + W_PG, vb, vG);
.LBB0_673:
	v_readlane_b32 s2, v232, 47
	v_readlane_b32 s3, v232, 48
	v_mov_b32_e32 v12, v186
	v_readlane_b32 s100, v231, 40
	s_cmpk_eq_u32 s48, 0xf0
	s_cselect_b32 s101, 0x50, 0
	s_add_i32 s100, s100, s101
	s_sub_i32 s101, s100, s48
	s_cmp_ge_u32 s100, s48
	s_cselect_b32 s100, s101, s100
	s_cmpk_lt_u32 s100, 0x40
	s_cselect_b64 s[2:3], -1, 0
	s_andn2_b64 vcc, exec, s[2:3]
	s_cbranch_vccnz .LBB0_678
	s_lshl_b64 s[2:3], s[40:41], 2
	v_ashrrev_i32_e32 v0, 1, v12
	s_add_u32 s2, s20, s2
	v_and_b32_e32 v49, 0xffffffe0, v0
	v_lshlrev_b32_e32 v0, 4, v12
	s_addc_u32 s3, s21, s3
	v_and_b32_e32 v0, 0x1f0, v0
	s_add_u32 s6, s18, s38
	v_and_b32_e32 v48, 63, v12
	v_and_b32_e32 v14, 0xffffffc0, v12
	v_add_u32_e32 v15, 0, v0
	v_lshl_add_u64 v[10:11], s[36:37], 0, v[0:1]
	v_ashrrev_i32_e32 v0, 5, v12
	v_add_u32_e32 v17, 0x200, v12
	v_add_u32_e32 v18, 0x400, v12
	v_add_u32_e32 v12, 0x600, v12
	s_addc_u32 s7, s19, s39
	s_movk_i32 s10, 0x204
	s_mov_b64 s[4:5], 0x2180000
	v_ashrrev_i32_e32 v50, 5, v17
	v_ashrrev_i32_e32 v51, 5, v18
	v_ashrrev_i32_e32 v52, 5, v12
	s_cmp_lg_u64 s[18:19], 0
	v_mad_u32_u24 v13, v48, s10, 0
	v_lshl_add_u64 v[10:11], v[10:11], 0, s[4:5]
	v_mul_lo_u32 v16, v0, s10
	v_mul_lo_u32 v17, v50, s10
	v_mul_lo_u32 v18, v51, s10
	v_mul_lo_u32 v12, v52, s10
	s_mov_b32 s4, s100
	s_cselect_b64 s[8:9], -1, 0
	s_lshl_b32 s12, s4, 6
	s_lshl_b32 s13, s48, 6
	v_add_u32_e32 v53, v13, v14
	v_add_u32_e32 v54, v15, v16
	v_add_u32_e32 v55, v15, v17
	v_add_u32_e32 v56, v15, v18
	v_add_u32_e32 v57, v15, v12
	s_mov_b32 s14, s4
	v_readlane_b32 s5, v231, 41
	s_branch .LBB0_676

; __device__ __forceinline__ int ltid() { int t = threadIdx.x; asm volatile("" : "+v"(t)); return t; }
; __device__ __forceinline__ void convert_job(unsigned char* smem, const float* src, int ld, int col0, int mapkind, int N, int K, const float* scale, bf16_t* dst, int vb, int vG) {
;     const int tidx = ltid();
;     bf16_t* tile = (bf16_t*)smem;
;     const int w = tidx >> 6, lane = tidx & 63;
;     const int tn = N / 64, tk = K / 256, ntile = tn * tk;
;     for (int t = vb; t < ntile; t += vG) {
;         const int n0 = (t % tn) * 64, k0 = (t / tn) * 256;
;         const int np = n0 + lane; int sc;
;         if (mapkind == 0) sc = col0 + np;
; __device__ __forceinline__ void convert_layer(unsigned char* smem, const Params& P, int layer, int skip) {
;     ...
;     convert_job(smem, P.w_ple_proj + (size_t)layer * 256 * DM, DM, 0, 0, DM, 256, nullptr, wb + W_PP, vb, vG);
.LBB0_678:
	v_mov_b32_e32 v16, v186
	v_readlane_b32 s100, v231, 40
	s_cmpk_eq_u32 s48, 0xf0
	s_cselect_b32 s101, 0x10, 0
	s_add_i32 s100, s100, s101
	s_sub_i32 s101, s100, s48
	s_cmp_ge_u32 s100, s48
	s_cselect_b32 s100, s101, s100
	s_cmpk_lt_u32 s100, 0x10
	s_cselect_b64 s[24:25], 0, -1
	s_and_b64 vcc, exec, s[24:25]
	s_cbranch_vccnz .LBB0_681
	v_ashrrev_i32_e32 v0, 1, v16
	v_and_b32_e32 v13, 0xffffffe0, v0
	v_lshlrev_b32_e32 v0, 4, v16
	v_and_b32_e32 v0, 0x1f0, v0
	v_and_b32_e32 v12, 63, v16
	v_and_b32_e32 v18, 0xffffffc0, v16
	v_add_u32_e32 v21, 0, v0
	v_lshl_add_u64 v[10:11], s[36:37], 0, v[0:1]
	v_ashrrev_i32_e32 v0, 5, v16
	v_add_u32_e32 v14, 0x200, v16
	v_add_u32_e32 v15, 0x400, v16
	v_add_u32_e32 v16, 0x600, v16
	s_movk_i32 s6, 0x204
	s_mov_b64 s[4:5], 0x2380000
	v_ashrrev_i32_e32 v14, 5, v14
	v_ashrrev_i32_e32 v15, 5, v15
	v_ashrrev_i32_e32 v16, 5, v16
	s_add_u32 s2, s22, s40
	v_mad_u32_u24 v17, v12, s6, 0
	v_lshl_add_u64 v[10:11], v[10:11], 0, s[4:5]
	v_mul_lo_u32 v19, v0, s6
	v_mul_lo_u32 v20, v14, s6
	v_mul_lo_u32 v22, v15, s6
	v_mul_lo_u32 v23, v16, s6
	s_mov_b32 s4, s100
	s_addc_u32 s3, s23, s41
	s_lshl_b32 s8, s4, 6
	s_lshl_b32 s9, s48, 6
	v_add_u32_e32 v17, v17, v18
	v_add_u32_e32 v18, v21, v19
	v_add_u32_e32 v19, v21, v20
	v_add_u32_e32 v20, v21, v22
	v_add_u32_e32 v21, v21, v23
	s_mov_b32 s10, s4
	v_readlane_b32 s5, v231, 41
